# P9 epilogue: non-temporal hint on the last-use x1 residual loads
# speedup vs baseline: 1.0050x; 1.0002x over previous
.Lp9_epi:
	s_lshl_b32 s19, s8, 8
	s_sub_i32 s8, s28, 32
	s_lshr_b32 s8, s8, 4
	s_mulk_i32 s8, 0x1800
	s_cmp_gt_i32 s28, 31
	v_lshl_add_u32 v82, s28, 8, v163
	s_cselect_b32 s8, s8, 0xc000
	v_ashrrev_i32_e32 v83, 31, v82
	s_ashr_i32 s21, s19, 31
	v_lshlrev_b64 v[82:83], 10, v[82:83]
	v_mov_b32_e32 v85, s21
	v_or_b32_e32 v84, s19, v148
	v_lshl_add_u64 v[82:83], v[82:83], 0, v[84:85]
	s_lshl_b64 s[30:31], s[8:9], 2
	v_lshlrev_b64 v[158:159], 1, v[82:83]
	v_or_b32_e32 v80, s19, v162
	s_add_u32 s30, s78, s30
	v_lshl_add_u64 v[160:161], s[76:77], 0, v[158:159]
	s_addc_u32 s31, s79, s31
	v_ashrrev_i32_e32 v81, 31, v80
	v_add_co_u32_e32 v82, vcc, s46, v160
	v_lshl_add_u64 v[80:81], v[80:81], 2, s[30:31]
	s_nop 0
	v_addc_co_u32_e32 v83, vcc, 0, v161, vcc
	global_load_dwordx4 v[170:173], v[160:161], off nt
	global_load_dwordx4 v[174:177], v[82:83], off nt
	v_add_co_u32_e32 v82, vcc, s56, v80
	v_lshl_add_u64 v[158:159], s[22:23], 0, v[158:159]
	s_nop 0
	v_addc_co_u32_e32 v83, vcc, 0, v81, vcc
	global_load_dwordx4 v[92:95], v[82:83], off nt
	v_lshl_add_u64 v[80:81], v[80:81], 0, s[16:17]
	global_load_dwordx4 v[88:91], v[80:81], off offset:16
	global_load_dwordx4 v[84:87], v[80:81], off offset:128
	s_nop 0
	global_load_dwordx4 v[80:83], v[80:81], off offset:144
	s_waitcnt vmcnt(0)
	v_lshlrev_b32_e32 v178, 16, v170
	v_and_b32_e32 v179, 0xffff0000, v170
	v_lshlrev_b32_e32 v170, 16, v171
	v_and_b32_e32 v171, 0xffff0000, v171
	v_lshlrev_b32_e32 v180, 16, v172
	v_and_b32_e32 v181, 0xffff0000, v172
	v_lshlrev_b32_e32 v172, 16, v173
	v_pk_mul_f32 v[142:143], v[142:143], v[94:95]
	v_pk_mul_f32 v[140:141], v[140:141], v[92:93]
	v_pk_mul_f32 v[138:139], v[138:139], v[90:91]
	v_pk_mul_f32 v[136:137], v[136:137], v[88:89]
	v_pk_mul_f32 v[134:135], v[134:135], v[86:87]
	v_pk_mul_f32 v[132:133], v[132:133], v[84:85]
	v_pk_mul_f32 v[186:187], v[130:131], v[82:83]
	v_pk_mul_f32 v[188:189], v[128:129], v[80:81]
	v_cvt_pk_bf16_f32 v128, v140, v141
	v_cvt_pk_bf16_f32 v129, v142, v143
	v_cvt_pk_bf16_f32 v130, v136, v137
	v_cvt_pk_bf16_f32 v131, v138, v139
	v_cvt_pk_bf16_f32 v132, v132, v133
	v_cvt_pk_bf16_f32 v133, v134, v135
	v_cvt_pk_bf16_f32 v134, v188, v189
	v_cvt_pk_bf16_f32 v135, v186, v187
	ds_write_b128 v167, v[128:131]
	ds_write_b128 v167, v[132:135] offset:64
	ds_read_b128 v[128:131], v168
	ds_read_b128 v[132:135], v168 offset:1152
	v_and_b32_e32 v173, 0xffff0000, v173
	v_lshlrev_b32_e32 v182, 16, v174
	v_and_b32_e32 v183, 0xffff0000, v174
	s_waitcnt lgkmcnt(1)
	v_lshlrev_b32_e32 v138, 16, v128
	v_and_b32_e32 v139, 0xffff0000, v128
	v_lshlrev_b32_e32 v128, 16, v129
	v_and_b32_e32 v129, 0xffff0000, v129
	v_lshlrev_b32_e32 v140, 16, v130
	v_and_b32_e32 v141, 0xffff0000, v130
	v_lshlrev_b32_e32 v130, 16, v131
	v_and_b32_e32 v131, 0xffff0000, v131
	v_lshlrev_b32_e32 v174, 16, v175
	v_and_b32_e32 v175, 0xffff0000, v175
	s_waitcnt lgkmcnt(0)
	v_lshlrev_b32_e32 v142, 16, v132
	v_and_b32_e32 v143, 0xffff0000, v132
	v_lshlrev_b32_e32 v132, 16, v133
	v_and_b32_e32 v133, 0xffff0000, v133
	v_pk_add_f32 v[170:171], v[170:171], v[128:129]
	v_pk_add_f32 v[128:129], v[178:179], v[138:139]
	v_pk_add_f32 v[138:139], v[172:173], v[130:131]
	v_pk_add_f32 v[130:131], v[180:181], v[140:141]
	v_lshlrev_b32_e32 v184, 16, v176
	v_and_b32_e32 v185, 0xffff0000, v176
	v_lshlrev_b32_e32 v136, 16, v177
	v_and_b32_e32 v137, 0xffff0000, v177
	v_lshlrev_b32_e32 v176, 16, v134
	v_and_b32_e32 v177, 0xffff0000, v134
	v_lshlrev_b32_e32 v134, 16, v135
	v_and_b32_e32 v135, 0xffff0000, v135
	v_pk_add_f32 v[132:133], v[174:175], v[132:133]
	v_cvt_pk_bf16_f32 v128, v128, v129
	v_cvt_pk_bf16_f32 v129, v170, v171
	v_cvt_pk_bf16_f32 v130, v130, v131
	v_cvt_pk_bf16_f32 v131, v138, v139
	v_pk_add_f32 v[140:141], v[182:183], v[142:143]
	v_pk_add_f32 v[134:135], v[136:137], v[134:135]
	global_store_dwordx4 v[158:159], v[128:131], off
	v_pk_mul_f32 v[126:127], v[126:127], v[94:95]
	v_pk_mul_f32 v[124:125], v[124:125], v[92:93]
	v_pk_add_f32 v[130:131], v[184:185], v[176:177]
	v_cvt_pk_bf16_f32 v129, v132, v133
	v_add_co_u32_e32 v132, vcc, s46, v158
	v_cvt_pk_bf16_f32 v128, v140, v141
	v_cvt_pk_bf16_f32 v130, v130, v131
	v_cvt_pk_bf16_f32 v131, v134, v135
	v_addc_co_u32_e32 v133, vcc, 0, v159, vcc
	global_store_dwordx4 v[132:133], v[128:131], off
	v_pk_mul_f32 v[122:123], v[122:123], v[90:91]
	v_pk_mul_f32 v[120:121], v[120:121], v[88:89]
	v_add_co_u32_e32 v128, vcc, s50, v160
	v_pk_mul_f32 v[118:119], v[118:119], v[86:87]
	s_nop 0
	v_addc_co_u32_e32 v129, vcc, 0, v161, vcc
	global_load_dwordx4 v[128:131], v[128:129], off nt
	v_add_co_u32_e32 v132, vcc, s55, v160
	v_pk_mul_f32 v[116:117], v[116:117], v[84:85]
	s_nop 0
	v_addc_co_u32_e32 v133, vcc, 0, v161, vcc
	global_load_dwordx4 v[132:135], v[132:133], off nt
	v_pk_mul_f32 v[136:137], v[114:115], v[82:83]
	v_pk_mul_f32 v[138:139], v[112:113], v[80:81]
	v_cvt_pk_bf16_f32 v112, v124, v125
	v_cvt_pk_bf16_f32 v113, v126, v127
	v_cvt_pk_bf16_f32 v114, v120, v121
	v_cvt_pk_bf16_f32 v115, v122, v123
	v_cvt_pk_bf16_f32 v116, v116, v117
	v_cvt_pk_bf16_f32 v117, v118, v119
	v_cvt_pk_bf16_f32 v118, v138, v139
	v_cvt_pk_bf16_f32 v119, v136, v137
	ds_write_b128 v167, v[112:115]
	ds_write_b128 v167, v[116:119] offset:64
	ds_read_b128 v[112:115], v168
	ds_read_b128 v[116:119], v168 offset:1152
	v_add_co_u32_e32 v120, vcc, s50, v158
	v_pk_mul_f32 v[110:111], v[110:111], v[94:95]
	s_waitcnt lgkmcnt(1)
	v_lshlrev_b32_e32 v122, 16, v112
	v_and_b32_e32 v123, 0xffff0000, v112
	v_lshlrev_b32_e32 v112, 16, v113
	v_and_b32_e32 v113, 0xffff0000, v113
	v_lshlrev_b32_e32 v124, 16, v114
	v_and_b32_e32 v125, 0xffff0000, v114
	v_lshlrev_b32_e32 v114, 16, v115
	v_and_b32_e32 v115, 0xffff0000, v115
	v_addc_co_u32_e32 v121, vcc, 0, v159, vcc
	s_waitcnt lgkmcnt(0)
	v_lshlrev_b32_e32 v126, 16, v116
	v_and_b32_e32 v127, 0xffff0000, v116
	v_lshlrev_b32_e32 v116, 16, v117
	v_and_b32_e32 v117, 0xffff0000, v117
	v_lshlrev_b32_e32 v136, 16, v118
	v_and_b32_e32 v137, 0xffff0000, v118
	v_pk_mul_f32 v[108:109], v[108:109], v[92:93]
	v_pk_mul_f32 v[106:107], v[106:107], v[90:91]
	v_pk_mul_f32 v[104:105], v[104:105], v[88:89]
	v_pk_mul_f32 v[102:103], v[102:103], v[86:87]
	v_pk_mul_f32 v[100:101], v[100:101], v[84:85]
	v_pk_mul_f32 v[78:79], v[78:79], v[94:95]
	v_cvt_pk_bf16_f32 v100, v100, v101
	v_cvt_pk_bf16_f32 v101, v102, v103
	v_pk_mul_f32 v[76:77], v[76:77], v[92:93]
	v_pk_mul_f32 v[74:75], v[74:75], v[90:91]
	v_pk_mul_f32 v[72:73], v[72:73], v[88:89]
	v_pk_mul_f32 v[70:71], v[70:71], v[86:87]
	v_pk_mul_f32 v[68:69], v[68:69], v[84:85]
	v_pk_mul_f32 v[62:63], v[62:63], v[94:95]
	v_cvt_pk_bf16_f32 v68, v68, v69
	v_cvt_pk_bf16_f32 v69, v70, v71
	v_pk_mul_f32 v[60:61], v[60:61], v[92:93]
	v_pk_mul_f32 v[58:59], v[58:59], v[90:91]
	v_pk_mul_f32 v[56:57], v[56:57], v[88:89]
	v_pk_mul_f32 v[54:55], v[54:55], v[86:87]
	v_pk_mul_f32 v[52:53], v[52:53], v[84:85]
	v_pk_mul_f32 v[46:47], v[46:47], v[94:95]
	v_cvt_pk_bf16_f32 v52, v52, v53
	v_cvt_pk_bf16_f32 v53, v54, v55
	v_pk_mul_f32 v[44:45], v[44:45], v[92:93]
	v_pk_mul_f32 v[42:43], v[42:43], v[90:91]
	v_pk_mul_f32 v[40:41], v[40:41], v[88:89]
	v_pk_mul_f32 v[38:39], v[38:39], v[86:87]
	v_pk_mul_f32 v[36:37], v[36:37], v[84:85]
	v_pk_mul_f32 v[30:31], v[30:31], v[94:95]
	v_cvt_pk_bf16_f32 v36, v36, v37
	v_cvt_pk_bf16_f32 v37, v38, v39
	v_pk_mul_f32 v[28:29], v[28:29], v[92:93]
	v_pk_mul_f32 v[26:27], v[26:27], v[90:91]
	v_pk_mul_f32 v[24:25], v[24:25], v[88:89]
	v_pk_mul_f32 v[22:23], v[22:23], v[86:87]
	v_pk_mul_f32 v[20:21], v[20:21], v[84:85]
	v_pk_mul_f32 v[14:15], v[14:15], v[94:95]
	v_cvt_pk_bf16_f32 v20, v20, v21
	v_cvt_pk_bf16_f32 v21, v22, v23
	v_pk_mul_f32 v[12:13], v[12:13], v[92:93]
	s_waitcnt vmcnt(1)
	v_lshlrev_b32_e32 v138, 16, v128
	v_and_b32_e32 v139, 0xffff0000, v128
	v_lshlrev_b32_e32 v128, 16, v129
	v_and_b32_e32 v129, 0xffff0000, v129
	v_lshlrev_b32_e32 v140, 16, v130
	v_and_b32_e32 v141, 0xffff0000, v130
	v_lshlrev_b32_e32 v130, 16, v131
	v_and_b32_e32 v131, 0xffff0000, v131
	v_pk_add_f32 v[128:129], v[128:129], v[112:113]
	v_pk_add_f32 v[112:113], v[138:139], v[122:123]
	v_pk_add_f32 v[122:123], v[130:131], v[114:115]
	v_pk_add_f32 v[114:115], v[140:141], v[124:125]
	s_waitcnt vmcnt(0)
	v_lshlrev_b32_e32 v142, 16, v132
	v_and_b32_e32 v143, 0xffff0000, v132
	v_lshlrev_b32_e32 v132, 16, v133
	v_and_b32_e32 v133, 0xffff0000, v133
	v_cvt_pk_bf16_f32 v112, v112, v113
	v_cvt_pk_bf16_f32 v113, v128, v129
	v_cvt_pk_bf16_f32 v114, v114, v115
	v_cvt_pk_bf16_f32 v115, v122, v123
	v_lshlrev_b32_e32 v170, 16, v134
	v_and_b32_e32 v171, 0xffff0000, v134
	v_lshlrev_b32_e32 v134, 16, v135
	v_and_b32_e32 v135, 0xffff0000, v135
	v_pk_add_f32 v[116:117], v[132:133], v[116:117]
	global_store_dwordx4 v[120:121], v[112:115], off
	v_pk_add_f32 v[124:125], v[142:143], v[126:127]
	v_pk_mul_f32 v[120:121], v[98:99], v[82:83]
	v_lshlrev_b32_e32 v112, 16, v119
	v_and_b32_e32 v113, 0xffff0000, v119
	v_pk_add_f32 v[118:119], v[134:135], v[112:113]
	v_pk_add_f32 v[114:115], v[170:171], v[136:137]
	v_cvt_pk_bf16_f32 v113, v116, v117
	v_add_co_u32_e32 v116, vcc, s55, v158
	v_cvt_pk_bf16_f32 v112, v124, v125
	v_cvt_pk_bf16_f32 v114, v114, v115
	v_cvt_pk_bf16_f32 v115, v118, v119
	v_addc_co_u32_e32 v117, vcc, 0, v159, vcc
	global_store_dwordx4 v[116:117], v[112:115], off
	v_pk_mul_f32 v[122:123], v[96:97], v[80:81]
	v_cvt_pk_bf16_f32 v96, v108, v109
	v_add_co_u32_e32 v112, vcc, s44, v160
	v_cvt_pk_bf16_f32 v97, v110, v111
	s_nop 0
	v_addc_co_u32_e32 v113, vcc, 0, v161, vcc
	global_load_dwordx4 v[112:115], v[112:113], off nt
	v_add_co_u32_e32 v116, vcc, s45, v160
	v_cvt_pk_bf16_f32 v98, v104, v105
	s_nop 0
	v_addc_co_u32_e32 v117, vcc, 0, v161, vcc
	global_load_dwordx4 v[116:119], v[116:117], off nt
	v_cvt_pk_bf16_f32 v99, v106, v107
	v_cvt_pk_bf16_f32 v102, v122, v123
	v_cvt_pk_bf16_f32 v103, v120, v121
	ds_write_b128 v167, v[96:99]
	ds_write_b128 v167, v[100:103] offset:64
	ds_read_b128 v[96:99], v168
	ds_read_b128 v[100:103], v168 offset:1152
	v_add_co_u32_e32 v104, vcc, s44, v158
	v_pk_mul_f32 v[10:11], v[10:11], v[90:91]
	s_waitcnt lgkmcnt(1)
	v_lshlrev_b32_e32 v106, 16, v96
	v_and_b32_e32 v107, 0xffff0000, v96
	v_lshlrev_b32_e32 v96, 16, v97
	v_and_b32_e32 v97, 0xffff0000, v97
	v_lshlrev_b32_e32 v108, 16, v98
	v_and_b32_e32 v109, 0xffff0000, v98
	v_lshlrev_b32_e32 v98, 16, v99
	v_and_b32_e32 v99, 0xffff0000, v99
	v_addc_co_u32_e32 v105, vcc, 0, v159, vcc
	s_waitcnt lgkmcnt(0)
	v_lshlrev_b32_e32 v110, 16, v100
	v_and_b32_e32 v111, 0xffff0000, v100
	v_lshlrev_b32_e32 v100, 16, v101
	v_and_b32_e32 v101, 0xffff0000, v101
	v_pk_mul_f32 v[8:9], v[8:9], v[88:89]
	v_pk_mul_f32 v[6:7], v[6:7], v[86:87]
	v_pk_mul_f32 v[4:5], v[4:5], v[84:85]
	s_waitcnt vmcnt(1)
	v_lshlrev_b32_e32 v120, 16, v112
	v_and_b32_e32 v121, 0xffff0000, v112
	v_lshlrev_b32_e32 v112, 16, v113
	v_and_b32_e32 v113, 0xffff0000, v113
	v_lshlrev_b32_e32 v122, 16, v114
	v_and_b32_e32 v123, 0xffff0000, v114
	v_lshlrev_b32_e32 v114, 16, v115
	v_and_b32_e32 v115, 0xffff0000, v115
	v_pk_add_f32 v[112:113], v[112:113], v[96:97]
	v_pk_add_f32 v[96:97], v[120:121], v[106:107]
	v_pk_add_f32 v[106:107], v[114:115], v[98:99]
	v_pk_add_f32 v[98:99], v[122:123], v[108:109]
	s_waitcnt vmcnt(0)
	v_lshlrev_b32_e32 v124, 16, v116
	v_and_b32_e32 v125, 0xffff0000, v116
	v_lshlrev_b32_e32 v116, 16, v117
	v_and_b32_e32 v117, 0xffff0000, v117
	v_cvt_pk_bf16_f32 v96, v96, v97
	v_cvt_pk_bf16_f32 v97, v112, v113
	v_cvt_pk_bf16_f32 v98, v98, v99
	v_cvt_pk_bf16_f32 v99, v106, v107
	v_lshlrev_b32_e32 v126, 16, v118
	v_and_b32_e32 v127, 0xffff0000, v118
	global_store_dwordx4 v[104:105], v[96:99], off
	v_lshlrev_b32_e32 v118, 16, v119
	v_and_b32_e32 v119, 0xffff0000, v119
	v_pk_add_f32 v[98:99], v[116:117], v[100:101]
	v_lshlrev_b32_e32 v100, 16, v102
	v_and_b32_e32 v101, 0xffff0000, v102
	v_pk_add_f32 v[96:97], v[124:125], v[110:111]
	v_lshlrev_b32_e32 v102, 16, v103
	v_and_b32_e32 v103, 0xffff0000, v103
	v_pk_add_f32 v[100:101], v[126:127], v[100:101]
	v_pk_add_f32 v[102:103], v[118:119], v[102:103]
	v_cvt_pk_bf16_f32 v96, v96, v97
	v_cvt_pk_bf16_f32 v97, v98, v99
	v_cvt_pk_bf16_f32 v98, v100, v101
	v_add_co_u32_e32 v100, vcc, s45, v158
	v_cvt_pk_bf16_f32 v99, v102, v103
	s_nop 0
	v_addc_co_u32_e32 v101, vcc, 0, v159, vcc
	global_store_dwordx4 v[100:101], v[96:99], off
	v_pk_mul_f32 v[104:105], v[66:67], v[82:83]
	v_pk_mul_f32 v[106:107], v[64:65], v[80:81]
	v_add_co_u32_e32 v96, vcc, s49, v160
	v_cvt_pk_bf16_f32 v64, v76, v77
	s_nop 0
	v_addc_co_u32_e32 v97, vcc, 0, v161, vcc
	global_load_dwordx4 v[96:99], v[96:97], off nt
	v_add_co_u32_e32 v100, vcc, s51, v160
	v_cvt_pk_bf16_f32 v65, v78, v79
	s_nop 0
	v_addc_co_u32_e32 v101, vcc, 0, v161, vcc
	global_load_dwordx4 v[100:103], v[100:101], off nt
	v_cvt_pk_bf16_f32 v66, v72, v73
	v_cvt_pk_bf16_f32 v67, v74, v75
	v_cvt_pk_bf16_f32 v70, v106, v107
	v_cvt_pk_bf16_f32 v71, v104, v105
	ds_write_b128 v167, v[64:67]
	ds_write_b128 v167, v[68:71] offset:64
	ds_read_b128 v[64:67], v168
	ds_read_b128 v[68:71], v168 offset:1152
	v_cvt_pk_bf16_f32 v4, v4, v5
	v_cvt_pk_bf16_f32 v5, v6, v7
	s_waitcnt lgkmcnt(1)
	v_lshlrev_b32_e32 v72, 16, v64
	v_and_b32_e32 v73, 0xffff0000, v64
	v_lshlrev_b32_e32 v64, 16, v65
	v_and_b32_e32 v65, 0xffff0000, v65
	v_lshlrev_b32_e32 v74, 16, v66
	v_and_b32_e32 v75, 0xffff0000, v66
	v_lshlrev_b32_e32 v66, 16, v67
	v_and_b32_e32 v67, 0xffff0000, v67
	s_waitcnt vmcnt(1)
	v_lshlrev_b32_e32 v76, 16, v96
	v_and_b32_e32 v77, 0xffff0000, v96
	v_lshlrev_b32_e32 v78, 16, v97
	v_and_b32_e32 v79, 0xffff0000, v97
	v_lshlrev_b32_e32 v96, 16, v98
	v_and_b32_e32 v97, 0xffff0000, v98
	v_lshlrev_b32_e32 v98, 16, v99
	v_and_b32_e32 v99, 0xffff0000, v99
	v_pk_add_f32 v[78:79], v[78:79], v[64:65]
	v_pk_add_f32 v[64:65], v[76:77], v[72:73]
	v_pk_add_f32 v[72:73], v[98:99], v[66:67]
	v_pk_add_f32 v[66:67], v[96:97], v[74:75]
	v_cvt_pk_bf16_f32 v64, v64, v65
	v_cvt_pk_bf16_f32 v66, v66, v67
	v_cvt_pk_bf16_f32 v67, v72, v73
	v_add_co_u32_e32 v72, vcc, s49, v158
	v_cvt_pk_bf16_f32 v65, v78, v79
	s_nop 0
	v_addc_co_u32_e32 v73, vcc, 0, v159, vcc
	s_waitcnt vmcnt(0)
	v_lshlrev_b32_e32 v104, 16, v100
	v_and_b32_e32 v105, 0xffff0000, v100
	v_lshlrev_b32_e32 v100, 16, v101
	v_and_b32_e32 v101, 0xffff0000, v101
	v_lshlrev_b32_e32 v106, 16, v102
	v_and_b32_e32 v107, 0xffff0000, v102
	global_store_dwordx4 v[72:73], v[64:67], off
	v_lshlrev_b32_e32 v102, 16, v103
	v_and_b32_e32 v103, 0xffff0000, v103
	s_waitcnt lgkmcnt(0)
	v_lshlrev_b32_e32 v64, 16, v68
	v_and_b32_e32 v65, 0xffff0000, v68
	v_lshlrev_b32_e32 v66, 16, v69
	v_and_b32_e32 v67, 0xffff0000, v69
	v_lshlrev_b32_e32 v68, 16, v70
	v_and_b32_e32 v69, 0xffff0000, v70
	v_pk_add_f32 v[66:67], v[100:101], v[66:67]
	v_pk_add_f32 v[64:65], v[104:105], v[64:65]
	v_lshlrev_b32_e32 v70, 16, v71
	v_and_b32_e32 v71, 0xffff0000, v71
	v_pk_add_f32 v[68:69], v[106:107], v[68:69]
	v_pk_add_f32 v[70:71], v[102:103], v[70:71]
	v_cvt_pk_bf16_f32 v64, v64, v65
	v_cvt_pk_bf16_f32 v65, v66, v67
	v_cvt_pk_bf16_f32 v66, v68, v69
	v_add_co_u32_e32 v68, vcc, s51, v158
	v_cvt_pk_bf16_f32 v67, v70, v71
	s_nop 0
	v_addc_co_u32_e32 v69, vcc, 0, v159, vcc
	global_store_dwordx4 v[68:69], v[64:67], off
	v_pk_mul_f32 v[72:73], v[50:51], v[82:83]
	v_pk_mul_f32 v[74:75], v[48:49], v[80:81]
	v_add_co_u32_e32 v64, vcc, s57, v160
	v_cvt_pk_bf16_f32 v48, v60, v61
	s_nop 0
	v_addc_co_u32_e32 v65, vcc, 0, v161, vcc
	global_load_dwordx4 v[64:67], v[64:65], off nt
	v_add_co_u32_e32 v68, vcc, s58, v160
	v_cvt_pk_bf16_f32 v49, v62, v63
	s_nop 0
	v_addc_co_u32_e32 v69, vcc, 0, v161, vcc
	global_load_dwordx4 v[68:71], v[68:69], off nt
	v_cvt_pk_bf16_f32 v50, v56, v57
	v_cvt_pk_bf16_f32 v51, v58, v59
	v_cvt_pk_bf16_f32 v54, v74, v75
	v_cvt_pk_bf16_f32 v55, v72, v73
	ds_write_b128 v167, v[48:51]
	ds_write_b128 v167, v[52:55] offset:64
	ds_read_b128 v[48:51], v168
	ds_read_b128 v[52:55], v168 offset:1152
	s_waitcnt lgkmcnt(1)
	v_lshlrev_b32_e32 v56, 16, v48
	v_and_b32_e32 v57, 0xffff0000, v48
	v_lshlrev_b32_e32 v48, 16, v49
	v_and_b32_e32 v49, 0xffff0000, v49
	v_lshlrev_b32_e32 v58, 16, v50
	v_and_b32_e32 v59, 0xffff0000, v50
	v_lshlrev_b32_e32 v50, 16, v51
	v_and_b32_e32 v51, 0xffff0000, v51
	s_waitcnt vmcnt(1)
	v_lshlrev_b32_e32 v60, 16, v64
	v_and_b32_e32 v61, 0xffff0000, v64
	v_lshlrev_b32_e32 v62, 16, v65
	v_and_b32_e32 v63, 0xffff0000, v65
	v_lshlrev_b32_e32 v64, 16, v66
	v_and_b32_e32 v65, 0xffff0000, v66
	v_lshlrev_b32_e32 v66, 16, v67
	v_and_b32_e32 v67, 0xffff0000, v67
	v_pk_add_f32 v[62:63], v[62:63], v[48:49]
	v_pk_add_f32 v[48:49], v[60:61], v[56:57]
	v_pk_add_f32 v[56:57], v[66:67], v[50:51]
	v_pk_add_f32 v[50:51], v[64:65], v[58:59]
	v_cvt_pk_bf16_f32 v48, v48, v49
	v_cvt_pk_bf16_f32 v50, v50, v51
	v_cvt_pk_bf16_f32 v51, v56, v57
	v_add_co_u32_e32 v56, vcc, s57, v158
	v_cvt_pk_bf16_f32 v49, v62, v63
	s_nop 0
	v_addc_co_u32_e32 v57, vcc, 0, v159, vcc
	s_waitcnt vmcnt(0)
	v_lshlrev_b32_e32 v72, 16, v68
	v_and_b32_e32 v73, 0xffff0000, v68
	v_lshlrev_b32_e32 v68, 16, v69
	v_and_b32_e32 v69, 0xffff0000, v69
	v_lshlrev_b32_e32 v74, 16, v70
	v_and_b32_e32 v75, 0xffff0000, v70
	global_store_dwordx4 v[56:57], v[48:51], off
	v_lshlrev_b32_e32 v70, 16, v71
	v_and_b32_e32 v71, 0xffff0000, v71
	s_waitcnt lgkmcnt(0)
	v_lshlrev_b32_e32 v48, 16, v52
	v_and_b32_e32 v49, 0xffff0000, v52
	v_lshlrev_b32_e32 v50, 16, v53
	v_and_b32_e32 v51, 0xffff0000, v53
	v_lshlrev_b32_e32 v52, 16, v54
	v_and_b32_e32 v53, 0xffff0000, v54
	v_pk_add_f32 v[50:51], v[68:69], v[50:51]
	v_pk_add_f32 v[48:49], v[72:73], v[48:49]
	v_lshlrev_b32_e32 v54, 16, v55
	v_and_b32_e32 v55, 0xffff0000, v55
	v_pk_add_f32 v[52:53], v[74:75], v[52:53]
	v_pk_add_f32 v[54:55], v[70:71], v[54:55]
	v_cvt_pk_bf16_f32 v48, v48, v49
	v_cvt_pk_bf16_f32 v49, v50, v51
	v_cvt_pk_bf16_f32 v50, v52, v53
	v_add_co_u32_e32 v52, vcc, s58, v158
	v_cvt_pk_bf16_f32 v51, v54, v55
	s_nop 0
	v_addc_co_u32_e32 v53, vcc, 0, v159, vcc
	global_store_dwordx4 v[52:53], v[48:51], off
	v_pk_mul_f32 v[56:57], v[34:35], v[82:83]
	v_pk_mul_f32 v[58:59], v[32:33], v[80:81]
	v_add_co_u32_e32 v48, vcc, s59, v160
	v_cvt_pk_bf16_f32 v32, v44, v45
	s_nop 0
	v_addc_co_u32_e32 v49, vcc, 0, v161, vcc
	global_load_dwordx4 v[48:51], v[48:49], off nt
	v_add_co_u32_e32 v52, vcc, s60, v160
	v_cvt_pk_bf16_f32 v33, v46, v47
	s_nop 0
	v_addc_co_u32_e32 v53, vcc, 0, v161, vcc
	global_load_dwordx4 v[52:55], v[52:53], off nt
	v_cvt_pk_bf16_f32 v34, v40, v41
	v_cvt_pk_bf16_f32 v35, v42, v43
	v_cvt_pk_bf16_f32 v38, v58, v59
	v_cvt_pk_bf16_f32 v39, v56, v57
	ds_write_b128 v167, v[32:35]
	ds_write_b128 v167, v[36:39] offset:64
	ds_read_b128 v[32:35], v168
	ds_read_b128 v[36:39], v168 offset:1152
	s_waitcnt lgkmcnt(1)
	v_lshlrev_b32_e32 v40, 16, v32
	v_and_b32_e32 v41, 0xffff0000, v32
	v_lshlrev_b32_e32 v32, 16, v33
	v_and_b32_e32 v33, 0xffff0000, v33
	v_lshlrev_b32_e32 v42, 16, v34
	v_and_b32_e32 v43, 0xffff0000, v34
	v_lshlrev_b32_e32 v34, 16, v35
	v_and_b32_e32 v35, 0xffff0000, v35
	s_waitcnt vmcnt(1)
	v_lshlrev_b32_e32 v44, 16, v48
	v_and_b32_e32 v45, 0xffff0000, v48
	v_lshlrev_b32_e32 v46, 16, v49
	v_and_b32_e32 v47, 0xffff0000, v49
	v_lshlrev_b32_e32 v48, 16, v50
	v_and_b32_e32 v49, 0xffff0000, v50
	v_lshlrev_b32_e32 v50, 16, v51
	v_and_b32_e32 v51, 0xffff0000, v51
	v_pk_add_f32 v[46:47], v[46:47], v[32:33]
	v_pk_add_f32 v[32:33], v[44:45], v[40:41]
	v_pk_add_f32 v[40:41], v[50:51], v[34:35]
	v_pk_add_f32 v[34:35], v[48:49], v[42:43]
	v_cvt_pk_bf16_f32 v32, v32, v33
	v_cvt_pk_bf16_f32 v34, v34, v35
	v_cvt_pk_bf16_f32 v35, v40, v41
	v_add_co_u32_e32 v40, vcc, s59, v158
	v_cvt_pk_bf16_f32 v33, v46, v47
	s_nop 0
	v_addc_co_u32_e32 v41, vcc, 0, v159, vcc
	s_waitcnt vmcnt(0)
	v_lshlrev_b32_e32 v56, 16, v52
	v_and_b32_e32 v57, 0xffff0000, v52
	v_lshlrev_b32_e32 v52, 16, v53
	v_and_b32_e32 v53, 0xffff0000, v53
	v_lshlrev_b32_e32 v58, 16, v54
	v_and_b32_e32 v59, 0xffff0000, v54
	global_store_dwordx4 v[40:41], v[32:35], off
	v_lshlrev_b32_e32 v54, 16, v55
	v_and_b32_e32 v55, 0xffff0000, v55
	s_waitcnt lgkmcnt(0)
	v_lshlrev_b32_e32 v32, 16, v36
	v_and_b32_e32 v33, 0xffff0000, v36
	v_lshlrev_b32_e32 v34, 16, v37
	v_and_b32_e32 v35, 0xffff0000, v37
	v_lshlrev_b32_e32 v36, 16, v38
	v_and_b32_e32 v37, 0xffff0000, v38
	v_pk_add_f32 v[34:35], v[52:53], v[34:35]
	v_pk_add_f32 v[32:33], v[56:57], v[32:33]
	v_lshlrev_b32_e32 v38, 16, v39
	v_and_b32_e32 v39, 0xffff0000, v39
	v_pk_add_f32 v[36:37], v[58:59], v[36:37]
	v_pk_add_f32 v[38:39], v[54:55], v[38:39]
	v_cvt_pk_bf16_f32 v32, v32, v33
	v_cvt_pk_bf16_f32 v33, v34, v35
	v_cvt_pk_bf16_f32 v34, v36, v37
	v_add_co_u32_e32 v36, vcc, s60, v158
	v_cvt_pk_bf16_f32 v35, v38, v39
	s_nop 0
	v_addc_co_u32_e32 v37, vcc, 0, v159, vcc
	global_store_dwordx4 v[36:37], v[32:35], off
	v_pk_mul_f32 v[40:41], v[18:19], v[82:83]
	v_pk_mul_f32 v[42:43], v[16:17], v[80:81]
	v_add_co_u32_e32 v32, vcc, s61, v160
	v_cvt_pk_bf16_f32 v16, v28, v29
	s_nop 0
	v_addc_co_u32_e32 v33, vcc, 0, v161, vcc
	global_load_dwordx4 v[32:35], v[32:33], off nt
	v_add_co_u32_e32 v36, vcc, s62, v160
	v_cvt_pk_bf16_f32 v17, v30, v31
	s_nop 0
	v_addc_co_u32_e32 v37, vcc, 0, v161, vcc
	global_load_dwordx4 v[36:39], v[36:37], off nt
	v_cvt_pk_bf16_f32 v18, v24, v25
	v_cvt_pk_bf16_f32 v19, v26, v27
	v_cvt_pk_bf16_f32 v22, v42, v43
	v_cvt_pk_bf16_f32 v23, v40, v41
	ds_write_b128 v167, v[16:19]
	ds_write_b128 v167, v[20:23] offset:64
	ds_read_b128 v[16:19], v168
	ds_read_b128 v[20:23], v168 offset:1152
	s_waitcnt lgkmcnt(1)
	v_lshlrev_b32_e32 v24, 16, v16
	v_and_b32_e32 v25, 0xffff0000, v16
	v_lshlrev_b32_e32 v16, 16, v17
	v_and_b32_e32 v17, 0xffff0000, v17
	s_waitcnt vmcnt(1)
	v_lshlrev_b32_e32 v26, 16, v32
	v_and_b32_e32 v27, 0xffff0000, v32
	v_lshlrev_b32_e32 v28, 16, v33
	v_and_b32_e32 v29, 0xffff0000, v33
	v_lshlrev_b32_e32 v30, 16, v34
	v_and_b32_e32 v31, 0xffff0000, v34
	v_lshlrev_b32_e32 v32, 16, v35
	v_and_b32_e32 v33, 0xffff0000, v35
	v_pk_add_f32 v[28:29], v[28:29], v[16:17]
	v_pk_add_f32 v[16:17], v[26:27], v[24:25]
	v_lshlrev_b32_e32 v24, 16, v18
	v_and_b32_e32 v25, 0xffff0000, v18
	v_lshlrev_b32_e32 v18, 16, v19
	v_and_b32_e32 v19, 0xffff0000, v19
	v_pk_add_f32 v[26:27], v[32:33], v[18:19]
	v_pk_add_f32 v[18:19], v[30:31], v[24:25]
	v_add_co_u32_e32 v24, vcc, s61, v158
	v_cvt_pk_bf16_f32 v16, v16, v17
	v_cvt_pk_bf16_f32 v17, v28, v29
	v_cvt_pk_bf16_f32 v18, v18, v19
	v_cvt_pk_bf16_f32 v19, v26, v27
	v_addc_co_u32_e32 v25, vcc, 0, v159, vcc
	s_waitcnt vmcnt(0)
	v_lshlrev_b32_e32 v34, 16, v36
	v_and_b32_e32 v35, 0xffff0000, v36
	v_lshlrev_b32_e32 v36, 16, v37
	v_and_b32_e32 v37, 0xffff0000, v37
	v_lshlrev_b32_e32 v40, 16, v38
	v_and_b32_e32 v41, 0xffff0000, v38
	global_store_dwordx4 v[24:25], v[16:19], off
	v_lshlrev_b32_e32 v38, 16, v39
	v_and_b32_e32 v39, 0xffff0000, v39
	s_waitcnt lgkmcnt(0)
	v_lshlrev_b32_e32 v16, 16, v20
	v_and_b32_e32 v17, 0xffff0000, v20
	v_lshlrev_b32_e32 v18, 16, v21
	v_and_b32_e32 v19, 0xffff0000, v21
	v_lshlrev_b32_e32 v20, 16, v22
	v_and_b32_e32 v21, 0xffff0000, v22
	v_pk_add_f32 v[18:19], v[36:37], v[18:19]
	v_pk_add_f32 v[16:17], v[34:35], v[16:17]
	v_lshlrev_b32_e32 v22, 16, v23
	v_and_b32_e32 v23, 0xffff0000, v23
	v_pk_add_f32 v[20:21], v[40:41], v[20:21]
	v_pk_add_f32 v[22:23], v[38:39], v[22:23]
	v_cvt_pk_bf16_f32 v16, v16, v17
	v_cvt_pk_bf16_f32 v17, v18, v19
	v_cvt_pk_bf16_f32 v18, v20, v21
	v_add_co_u32_e32 v20, vcc, s62, v158
	v_cvt_pk_bf16_f32 v19, v22, v23
	s_nop 0
	v_addc_co_u32_e32 v21, vcc, 0, v159, vcc
	global_store_dwordx4 v[20:21], v[16:19], off
	v_pk_mul_f32 v[24:25], v[2:3], v[82:83]
	v_pk_mul_f32 v[26:27], v[0:1], v[80:81]
	v_add_co_u32_e32 v16, vcc, s63, v160
	v_cvt_pk_bf16_f32 v0, v12, v13
	s_nop 0
	v_addc_co_u32_e32 v17, vcc, 0, v161, vcc
	global_load_dwordx4 v[16:19], v[16:17], off nt
	v_add_co_u32_e32 v20, vcc, s64, v160
	v_cvt_pk_bf16_f32 v1, v14, v15
	s_nop 0
	v_addc_co_u32_e32 v21, vcc, 0, v161, vcc
	global_load_dwordx4 v[20:23], v[20:21], off nt
	v_cvt_pk_bf16_f32 v2, v8, v9
	v_cvt_pk_bf16_f32 v3, v10, v11
	v_cvt_pk_bf16_f32 v6, v26, v27
	v_cvt_pk_bf16_f32 v7, v24, v25
	ds_write_b128 v167, v[0:3]
	ds_write_b128 v167, v[4:7] offset:64
	ds_read_b128 v[0:3], v168
	ds_read_b128 v[4:7], v168 offset:1152
	s_waitcnt lgkmcnt(1)
	v_lshlrev_b32_e32 v8, 16, v0
	v_and_b32_e32 v9, 0xffff0000, v0
	v_lshlrev_b32_e32 v0, 16, v1
	v_and_b32_e32 v1, 0xffff0000, v1
	s_waitcnt vmcnt(1)
	v_lshlrev_b32_e32 v10, 16, v16
	v_and_b32_e32 v11, 0xffff0000, v16
	v_lshlrev_b32_e32 v12, 16, v17
	v_and_b32_e32 v13, 0xffff0000, v17
	v_lshlrev_b32_e32 v14, 16, v18
	v_and_b32_e32 v15, 0xffff0000, v18
	v_lshlrev_b32_e32 v16, 16, v19
	v_and_b32_e32 v17, 0xffff0000, v19
	v_pk_add_f32 v[12:13], v[12:13], v[0:1]
	v_pk_add_f32 v[0:1], v[10:11], v[8:9]
	v_lshlrev_b32_e32 v8, 16, v2
	v_and_b32_e32 v9, 0xffff0000, v2
	v_lshlrev_b32_e32 v2, 16, v3
	v_and_b32_e32 v3, 0xffff0000, v3
	v_pk_add_f32 v[10:11], v[16:17], v[2:3]
	v_pk_add_f32 v[2:3], v[14:15], v[8:9]
	v_add_co_u32_e32 v8, vcc, s63, v158
	v_cvt_pk_bf16_f32 v0, v0, v1
	v_cvt_pk_bf16_f32 v1, v12, v13
	v_cvt_pk_bf16_f32 v2, v2, v3
	v_cvt_pk_bf16_f32 v3, v10, v11
	v_addc_co_u32_e32 v9, vcc, 0, v159, vcc
	s_waitcnt vmcnt(0)
	v_lshlrev_b32_e32 v18, 16, v20
	v_and_b32_e32 v19, 0xffff0000, v20
	v_lshlrev_b32_e32 v20, 16, v21
	v_and_b32_e32 v21, 0xffff0000, v21
	v_lshlrev_b32_e32 v24, 16, v22
	v_and_b32_e32 v25, 0xffff0000, v22
	global_store_dwordx4 v[8:9], v[0:3], off
	v_lshlrev_b32_e32 v22, 16, v23
	v_and_b32_e32 v23, 0xffff0000, v23
	s_waitcnt lgkmcnt(0)
	v_lshlrev_b32_e32 v0, 16, v4
	v_and_b32_e32 v1, 0xffff0000, v4
	v_lshlrev_b32_e32 v2, 16, v5
	v_and_b32_e32 v3, 0xffff0000, v5
	v_lshlrev_b32_e32 v4, 16, v6
	v_and_b32_e32 v5, 0xffff0000, v6
	v_pk_add_f32 v[2:3], v[20:21], v[2:3]
	v_pk_add_f32 v[0:1], v[18:19], v[0:1]
	v_pk_add_f32 v[4:5], v[24:25], v[4:5]
	v_lshlrev_b32_e32 v6, 16, v7
	v_and_b32_e32 v7, 0xffff0000, v7
	v_cvt_pk_bf16_f32 v0, v0, v1
	v_cvt_pk_bf16_f32 v1, v2, v3
	v_cvt_pk_bf16_f32 v2, v4, v5
	v_add_co_u32_e32 v4, vcc, 0x5c000, v158
	v_pk_add_f32 v[6:7], v[22:23], v[6:7]
	s_nop 0
	v_addc_co_u32_e32 v5, vcc, 0, v159, vcc
	v_cvt_pk_bf16_f32 v3, v6, v7
	s_andn2_b64 vcc, exec, s[0:1]
	s_mov_b64 s[0:1], -1
	global_store_dwordx4 v[4:5], v[0:3], off
	s_cbranch_vccnz .LBB0_958
	s_andn2_b64 vcc, exec, s[10:11]
	s_cbranch_vccnz .LBB0_957
	s_barrier
	s_branch .LBB0_957
